# MFMA/VALU interleave: PV MFMAs of column group 0 issued in the shadow of column group 1's exponentials (SEL c3 and WIN interior steps)
# baseline (speedup 1.0000x reference)
; template <int CGM>
; __device__ __forceinline__ void pv2(f32x4 (&o)[2][4], const float (&p)[2][4][4], const unsigned char* Vs, int r, int fq) {
;     bf16x8 pb[2][2];
; #pragma unroll
;     for (int cg_ = 0; cg_ < 2; ++cg_) if ((CGM >> cg_) & 1)
; #pragma unroll
;         for (int kc = 0; kc < 2; ++kc) {
;             u32x4 w; w.x = cvt_pk_bf16(p[cg_][2 * kc][0], p[cg_][2 * kc][1]); w.y = cvt_pk_bf16(p[cg_][2 * kc][2], p[cg_][2 * kc][3]);
;             w.z = cvt_pk_bf16(p[cg_][2 * kc + 1][0], p[cg_][2 * kc + 1][1]); w.w = cvt_pk_bf16(p[cg_][2 * kc + 1][2], p[cg_][2 * kc + 1][3]);
;             pb[cg_][kc] = __builtin_bit_cast(bf16x8, w);
;         }
; #pragma unroll
;     for (int df = 0; df < 4; ++df)
; #pragma unroll
;         for (int kc = 0; kc < 2; ++kc) {
;             const int R = prow(df, r);
;             const bf16x8 vf = *(const bf16x8*)(Vs + R * 128 + (((4 * kc + fq) ^ swz(R)) << 4));
;             if (CGM & 1) o[0][df] = __builtin_amdgcn_mfma_f32_16x16x32_bf16(vf, pb[0][kc], o[0][df], 0, 0, 0);
; template <int CGM>
; __device__ __forceinline__ void step_int(const bf16x8 (&kf)[4][2], const bf16x8 (&q)[2][2], float farb, const bool (&selq)[2],
;                                          float (&m)[2], float (&l)[2], f32x4 (&o)[2][4], const unsigned char* Vs, int r, int fq) {
;     f32x4 s[2][4]; float mx[2] = {-1e30f, -1e30f};
; #pragma unroll
;     for (int cg_ = 0; cg_ < 2; ++cg_) if ((CGM >> cg_) & 1) { qk(s[cg_], kf, q[cg_], selq[cg_] ? farb - m[cg_] : -1e30f); mx[cg_] = red_max4(max16v(s[cg_])); }
;     if (__any(mx[0] > 0.f || mx[1] > 0.f)) {
; #pragma unroll
;         for (int cg_ = 0; cg_ < 2; ++cg_) if ((CGM >> cg_) & 1) {
;             const float d = fmaxf(mx[cg_], 0.f), sc = __builtin_amdgcn_exp2f(-d); m[cg_] += d; l[cg_] *= sc;
; #pragma unroll
;             for (int df = 0; df < 4; ++df) o[cg_][df] *= sc;
; #pragma unroll
;             for (int f = 0; f < 4; ++f) s[cg_][f] -= d;
;         }
;     }
;     float p[2][4][4];
; #pragma unroll
;     for (int cg_ = 0; cg_ < 2; ++cg_) if ((CGM >> cg_) & 1) {
;         float rs = 0.f;
; #pragma unroll
;         for (int f = 0; f < 4; ++f)
; #pragma unroll
;             for (int i = 0; i < 4; ++i) { const float pe = __builtin_amdgcn_exp2f(s[cg_][f][i]); p[cg_][f][i] = pe; rs += pe; }
;         l[cg_] += rs;
;     }
;     pv2<CGM>(o, p, Vs, r, fq);
; }
.Lsel_c3:
	v_sub_f32_e32 v128, v18, v124
	v_sub_f32_e32 v144, v18, v125
	v_cndmask_b32_e64 v128, v148, v128, s[10:11]
	v_cndmask_b32_e64 v144, v148, v144, s[8:9]
	v_mov_b32_e32 v129, v128
	v_mov_b32_e32 v145, v144
	v_mov_b64_e32 v[130:131], v[128:129]
	v_mov_b64_e32 v[146:147], v[144:145]
	s_waitcnt lgkmcnt(7)
	v_mfma_f32_16x16x32_bf16 v[92:95], v[88:91], v[2:5], v[128:131]
	v_mfma_f32_16x16x32_bf16 v[108:111], v[88:91], v[10:13], v[144:147]
	s_waitcnt lgkmcnt(6)
	v_mfma_f32_16x16x32_bf16 v[96:99], v[80:83], v[2:5], v[128:131]
	v_mfma_f32_16x16x32_bf16 v[112:115], v[80:83], v[10:13], v[144:147]
	s_waitcnt lgkmcnt(5)
	v_mfma_f32_16x16x32_bf16 v[92:95], v[84:87], v[6:9], v[92:95]
	v_mfma_f32_16x16x32_bf16 v[108:111], v[84:87], v[14:17], v[108:111]
	s_waitcnt lgkmcnt(4)
	v_mfma_f32_16x16x32_bf16 v[96:99], v[76:79], v[6:9], v[96:99]
	v_mfma_f32_16x16x32_bf16 v[112:115], v[76:79], v[14:17], v[112:115]
	s_waitcnt lgkmcnt(3)
	v_mfma_f32_16x16x32_bf16 v[100:103], v[72:75], v[2:5], v[128:131]
	v_mfma_f32_16x16x32_bf16 v[116:119], v[72:75], v[10:13], v[144:147]
	s_waitcnt lgkmcnt(2)
	v_mfma_f32_16x16x32_bf16 v[104:107], v[60:63], v[2:5], v[128:131]
	v_mfma_f32_16x16x32_bf16 v[120:123], v[60:63], v[10:13], v[144:147]
	s_waitcnt lgkmcnt(1)
	v_mfma_f32_16x16x32_bf16 v[100:103], v[68:71], v[6:9], v[100:103]
	v_mfma_f32_16x16x32_bf16 v[116:119], v[68:71], v[14:17], v[116:119]
	s_waitcnt lgkmcnt(0)
	v_mfma_f32_16x16x32_bf16 v[104:107], v[64:67], v[6:9], v[104:107]
	v_mfma_f32_16x16x32_bf16 v[120:123], v[64:67], v[14:17], v[120:123]
	ds_read_b128 v[88:91], v143 offset:8192
	ds_read_b128 v[80:83], v143 offset:8704
	ds_read_b128 v[72:75], v143 offset:12288
	ds_read_b128 v[60:63], v143 offset:12800
	ds_read_b128 v[84:87], v142 offset:8192
	ds_read_b128 v[76:79], v142 offset:8704
	ds_read_b128 v[68:71], v142 offset:12288
	ds_read_b128 v[64:67], v142 offset:12800
.Lsel_c3_e0:
	v_exp_f32_e32 v232, v92
	v_exp_f32_e32 v233, v93
	v_exp_f32_e32 v234, v94
	v_exp_f32_e32 v235, v95
	v_exp_f32_e32 v236, v96
	v_exp_f32_e32 v237, v97
	v_exp_f32_e32 v238, v98
	v_exp_f32_e32 v239, v99
	v_exp_f32_e32 v240, v100
	v_exp_f32_e32 v241, v101
	v_exp_f32_e32 v242, v102
	v_exp_f32_e32 v243, v103
	v_exp_f32_e32 v244, v104
	v_exp_f32_e32 v245, v105
	v_exp_f32_e32 v246, v106
	v_exp_f32_e32 v247, v107
	v_pk_add_f32 v[130:131], v[232:233], v[234:235]
	v_pk_add_f32 v[130:131], v[130:131], v[236:237]
	v_pk_add_f32 v[130:131], v[130:131], v[238:239]
	v_pk_add_f32 v[130:131], v[130:131], v[240:241]
	v_pk_add_f32 v[130:131], v[130:131], v[242:243]
	v_pk_add_f32 v[130:131], v[130:131], v[244:245]
	v_pk_add_f32 v[130:131], v[130:131], v[246:247]
	v_add_f32_e32 v130, v130, v131
	v_cmp_lt_f32_e32 vcc, 0x42800000, v130
	s_cbranch_vccnz .Lsel_c3_s0
	v_add_f32_e32 v127, v127, v130
	v_cvt_pk_bf16_f32 v92, v232, v233
	v_cvt_pk_bf16_f32 v93, v234, v235
	v_cvt_pk_bf16_f32 v94, v236, v237
	v_cvt_pk_bf16_f32 v95, v238, v239
	v_cvt_pk_bf16_f32 v96, v240, v241
	v_cvt_pk_bf16_f32 v97, v242, v243
	v_cvt_pk_bf16_f32 v98, v244, v245
	v_cvt_pk_bf16_f32 v99, v246, v247
	s_waitcnt lgkmcnt(0)
	s_nop 0
.Lsel_c3_e1:
	v_exp_f32_e32 v232, v108
	v_exp_f32_e32 v233, v109
	v_mfma_f32_16x16x32_bf16 v[56:59], v[88:91], v[92:95], v[56:59]
	v_exp_f32_e32 v234, v110
	v_exp_f32_e32 v235, v111
	v_mfma_f32_16x16x32_bf16 v[52:55], v[80:83], v[92:95], v[52:55]
	v_exp_f32_e32 v236, v112
	v_exp_f32_e32 v237, v113
	v_mfma_f32_16x16x32_bf16 v[48:51], v[72:75], v[92:95], v[48:51]
	v_exp_f32_e32 v238, v114
	v_exp_f32_e32 v239, v115
	v_mfma_f32_16x16x32_bf16 v[44:47], v[60:63], v[92:95], v[44:47]
	v_exp_f32_e32 v240, v116
	v_exp_f32_e32 v241, v117
	v_mfma_f32_16x16x32_bf16 v[56:59], v[84:87], v[96:99], v[56:59]
	v_exp_f32_e32 v242, v118
	v_exp_f32_e32 v243, v119
	v_mfma_f32_16x16x32_bf16 v[52:55], v[76:79], v[96:99], v[52:55]
	v_exp_f32_e32 v244, v120
	v_exp_f32_e32 v245, v121
	v_mfma_f32_16x16x32_bf16 v[48:51], v[68:71], v[96:99], v[48:51]
	v_exp_f32_e32 v246, v122
	v_exp_f32_e32 v247, v123
	v_mfma_f32_16x16x32_bf16 v[44:47], v[64:67], v[96:99], v[44:47]
	v_pk_add_f32 v[146:147], v[232:233], v[234:235]
	v_pk_add_f32 v[146:147], v[146:147], v[236:237]
	v_pk_add_f32 v[146:147], v[146:147], v[238:239]
	v_pk_add_f32 v[146:147], v[146:147], v[240:241]
	v_pk_add_f32 v[146:147], v[146:147], v[242:243]
	v_pk_add_f32 v[146:147], v[146:147], v[244:245]
	v_pk_add_f32 v[146:147], v[146:147], v[246:247]
	v_add_f32_e32 v146, v146, v147
	v_cmp_lt_f32_e32 vcc, 0x42800000, v146
	s_cbranch_vccnz .Lsel_c3_s1
	v_add_f32_e32 v126, v126, v146
	v_cvt_pk_bf16_f32 v108, v232, v233
	v_cvt_pk_bf16_f32 v109, v234, v235
	v_cvt_pk_bf16_f32 v110, v236, v237
	v_cvt_pk_bf16_f32 v111, v238, v239
	v_cvt_pk_bf16_f32 v112, v240, v241
	v_cvt_pk_bf16_f32 v113, v242, v243
	v_cvt_pk_bf16_f32 v114, v244, v245
	v_cvt_pk_bf16_f32 v115, v246, v247
.Lsel_c3_p1:
	s_nop 0
	v_mfma_f32_16x16x32_bf16 v[40:43], v[88:91], v[108:111], v[40:43]
	v_mfma_f32_16x16x32_bf16 v[28:31], v[80:83], v[108:111], v[28:31]
	v_mfma_f32_16x16x32_bf16 v[24:27], v[72:75], v[108:111], v[24:27]
	v_mfma_f32_16x16x32_bf16 v[20:23], v[60:63], v[108:111], v[20:23]
	v_mfma_f32_16x16x32_bf16 v[40:43], v[84:87], v[112:115], v[40:43]
	v_mfma_f32_16x16x32_bf16 v[28:31], v[76:79], v[112:115], v[28:31]
	v_mfma_f32_16x16x32_bf16 v[24:27], v[68:71], v[112:115], v[24:27]
	v_mfma_f32_16x16x32_bf16 v[20:23], v[64:67], v[112:115], v[20:23]
	s_branch .LBB0_2481
.Lsel_c3_e1b:
	v_exp_f32_e32 v232, v108
	v_exp_f32_e32 v233, v109
	v_exp_f32_e32 v234, v110
	v_exp_f32_e32 v235, v111
	v_exp_f32_e32 v236, v112
	v_exp_f32_e32 v237, v113
	v_exp_f32_e32 v238, v114
	v_exp_f32_e32 v239, v115
	v_exp_f32_e32 v240, v116
	v_exp_f32_e32 v241, v117
	v_exp_f32_e32 v242, v118
	v_exp_f32_e32 v243, v119
	v_exp_f32_e32 v244, v120
	v_exp_f32_e32 v245, v121
	v_exp_f32_e32 v246, v122
	v_exp_f32_e32 v247, v123
	v_pk_add_f32 v[146:147], v[232:233], v[234:235]
	v_pk_add_f32 v[146:147], v[146:147], v[236:237]
	v_pk_add_f32 v[146:147], v[146:147], v[238:239]
	v_pk_add_f32 v[146:147], v[146:147], v[240:241]
	v_pk_add_f32 v[146:147], v[146:147], v[242:243]
	v_pk_add_f32 v[146:147], v[146:147], v[244:245]
	v_pk_add_f32 v[146:147], v[146:147], v[246:247]
	v_add_f32_e32 v146, v146, v147
	v_cmp_lt_f32_e32 vcc, 0x42800000, v146
	s_cbranch_vccnz .Lsel_c3_s1
	v_add_f32_e32 v126, v126, v146
	v_cvt_pk_bf16_f32 v108, v232, v233
	v_cvt_pk_bf16_f32 v109, v234, v235
	v_cvt_pk_bf16_f32 v110, v236, v237
	v_cvt_pk_bf16_f32 v111, v238, v239
	v_cvt_pk_bf16_f32 v112, v240, v241
	v_cvt_pk_bf16_f32 v113, v242, v243
	v_cvt_pk_bf16_f32 v114, v244, v245
	v_cvt_pk_bf16_f32 v115, v246, v247
	s_branch .Lsel_c3_p1

; template <int CGM>
; __device__ __forceinline__ void pv2(f32x4 (&o)[2][4], const float (&p)[2][4][4], const unsigned char* Vs, int r, int fq) {
;     bf16x8 pb[2][2];
; #pragma unroll
;     for (int cg_ = 0; cg_ < 2; ++cg_) if ((CGM >> cg_) & 1)
; #pragma unroll
;         for (int kc = 0; kc < 2; ++kc) {
;             u32x4 w; w.x = cvt_pk_bf16(p[cg_][2 * kc][0], p[cg_][2 * kc][1]); w.y = cvt_pk_bf16(p[cg_][2 * kc][2], p[cg_][2 * kc][3]);
;             w.z = cvt_pk_bf16(p[cg_][2 * kc + 1][0], p[cg_][2 * kc + 1][1]); w.w = cvt_pk_bf16(p[cg_][2 * kc + 1][2], p[cg_][2 * kc + 1][3]);
;             pb[cg_][kc] = __builtin_bit_cast(bf16x8, w);
;         }
; #pragma unroll
;     for (int df = 0; df < 4; ++df)
; #pragma unroll
;         for (int kc = 0; kc < 2; ++kc) {
;             const int R = prow(df, r);
;             const bf16x8 vf = *(const bf16x8*)(Vs + R * 128 + (((4 * kc + fq) ^ swz(R)) << 4));
;             if (CGM & 1) o[0][df] = __builtin_amdgcn_mfma_f32_16x16x32_bf16(vf, pb[0][kc], o[0][df], 0, 0, 0);
; template <int CGM>
; __device__ __forceinline__ void step_int(const bf16x8 (&kf)[4][2], const bf16x8 (&q)[2][2], float farb, const bool (&selq)[2],
;                                          float (&m)[2], float (&l)[2], f32x4 (&o)[2][4], const unsigned char* Vs, int r, int fq) {
;     f32x4 s[2][4]; float mx[2] = {-1e30f, -1e30f};
; #pragma unroll
;     for (int cg_ = 0; cg_ < 2; ++cg_) if ((CGM >> cg_) & 1) { qk(s[cg_], kf, q[cg_], selq[cg_] ? farb - m[cg_] : -1e30f); mx[cg_] = red_max4(max16v(s[cg_])); }
;     if (__any(mx[0] > 0.f || mx[1] > 0.f)) {
; #pragma unroll
;         for (int cg_ = 0; cg_ < 2; ++cg_) if ((CGM >> cg_) & 1) {
;             const float d = fmaxf(mx[cg_], 0.f), sc = __builtin_amdgcn_exp2f(-d); m[cg_] += d; l[cg_] *= sc;
; #pragma unroll
;             for (int df = 0; df < 4; ++df) o[cg_][df] *= sc;
; #pragma unroll
;             for (int f = 0; f < 4; ++f) s[cg_][f] -= d;
;         }
;     }
;     float p[2][4][4];
; #pragma unroll
;     for (int cg_ = 0; cg_ < 2; ++cg_) if ((CGM >> cg_) & 1) {
;         float rs = 0.f;
; #pragma unroll
;         for (int f = 0; f < 4; ++f)
; #pragma unroll
;             for (int i = 0; i < 4; ++i) { const float pe = __builtin_amdgcn_exp2f(s[cg_][f][i]); p[cg_][f][i] = pe; rs += pe; }
;         l[cg_] += rs;
;     }
;     pv2<CGM>(o, p, Vs, r, fq);
; }
.Lwin_int:
	v_sub_f32_e32 v188, v18, v156
	v_sub_f32_e32 v192, v18, v157
	v_mov_b32_e32 v189, v188
	v_mov_b32_e32 v193, v192
	v_mov_b64_e32 v[190:191], v[188:189]
	v_mov_b64_e32 v[194:195], v[192:193]
	s_waitcnt lgkmcnt(7)
	v_mfma_f32_16x16x32_bf16 v[116:119], v[80:83], v[2:5], v[188:191]
	v_mfma_f32_16x16x32_bf16 v[136:139], v[80:83], v[10:13], v[192:195]
	s_waitcnt lgkmcnt(6)
	v_mfma_f32_16x16x32_bf16 v[120:123], v[72:75], v[2:5], v[188:191]
	v_mfma_f32_16x16x32_bf16 v[140:143], v[72:75], v[10:13], v[192:195]
	s_waitcnt lgkmcnt(5)
	v_mfma_f32_16x16x32_bf16 v[116:119], v[76:79], v[6:9], v[116:119]
	v_mfma_f32_16x16x32_bf16 v[136:139], v[76:79], v[14:17], v[136:139]
	s_waitcnt lgkmcnt(4)
	v_mfma_f32_16x16x32_bf16 v[120:123], v[68:71], v[6:9], v[120:123]
	v_mfma_f32_16x16x32_bf16 v[140:143], v[68:71], v[14:17], v[140:143]
	s_waitcnt lgkmcnt(3)
	v_mfma_f32_16x16x32_bf16 v[124:127], v[60:63], v[2:5], v[188:191]
	v_mfma_f32_16x16x32_bf16 v[144:147], v[60:63], v[10:13], v[192:195]
	s_waitcnt lgkmcnt(2)
	v_mfma_f32_16x16x32_bf16 v[132:135], v[56:59], v[2:5], v[188:191]
	v_mfma_f32_16x16x32_bf16 v[184:187], v[56:59], v[10:13], v[192:195]
	s_waitcnt lgkmcnt(1)
	v_mfma_f32_16x16x32_bf16 v[124:127], v[64:67], v[6:9], v[124:127]
	v_mfma_f32_16x16x32_bf16 v[144:147], v[64:67], v[14:17], v[144:147]
	s_waitcnt lgkmcnt(0)
	v_mfma_f32_16x16x32_bf16 v[132:135], v[52:55], v[6:9], v[132:135]
	v_mfma_f32_16x16x32_bf16 v[184:187], v[52:55], v[14:17], v[184:187]
	ds_read_b128 v[80:83], v149 offset:8192
	ds_read_b128 v[72:75], v149 offset:8704
	ds_read_b128 v[60:63], v149 offset:12288
	ds_read_b128 v[56:59], v149 offset:12800
	ds_read_b128 v[76:79], v182 offset:8192
	ds_read_b128 v[68:71], v182 offset:8704
	ds_read_b128 v[64:67], v182 offset:12288
	ds_read_b128 v[52:55], v182 offset:12800
.Lwin_int_e0:
	v_exp_f32_e32 v232, v116
	v_exp_f32_e32 v233, v117
	v_exp_f32_e32 v234, v118
	v_exp_f32_e32 v235, v119
	v_exp_f32_e32 v236, v120
	v_exp_f32_e32 v237, v121
	v_exp_f32_e32 v238, v122
	v_exp_f32_e32 v239, v123
	v_exp_f32_e32 v240, v124
	v_exp_f32_e32 v241, v125
	v_exp_f32_e32 v242, v126
	v_exp_f32_e32 v243, v127
	v_exp_f32_e32 v244, v132
	v_exp_f32_e32 v245, v133
	v_exp_f32_e32 v246, v134
	v_exp_f32_e32 v247, v135
	v_pk_add_f32 v[190:191], v[232:233], v[234:235]
	v_pk_add_f32 v[190:191], v[190:191], v[236:237]
	v_pk_add_f32 v[190:191], v[190:191], v[238:239]
	v_pk_add_f32 v[190:191], v[190:191], v[240:241]
	v_pk_add_f32 v[190:191], v[190:191], v[242:243]
	v_pk_add_f32 v[190:191], v[190:191], v[244:245]
	v_pk_add_f32 v[190:191], v[190:191], v[246:247]
	v_add_f32_e32 v190, v190, v191
	v_cmp_lt_f32_e32 vcc, 0x42800000, v190
	s_cbranch_vccnz .Lwin_int_s0
	v_add_f32_e32 v129, v155, v190
	v_cvt_pk_bf16_f32 v116, v232, v233
	v_cvt_pk_bf16_f32 v117, v234, v235
	v_cvt_pk_bf16_f32 v118, v236, v237
	v_cvt_pk_bf16_f32 v119, v238, v239
	v_cvt_pk_bf16_f32 v120, v240, v241
	v_cvt_pk_bf16_f32 v121, v242, v243
	v_cvt_pk_bf16_f32 v122, v244, v245
	v_cvt_pk_bf16_f32 v123, v246, v247
	s_waitcnt lgkmcnt(0)
	s_nop 0
.Lwin_int_e1:
	v_exp_f32_e32 v232, v136
	v_exp_f32_e32 v233, v137
	v_mfma_f32_16x16x32_bf16 v[48:51], v[80:83], v[116:119], v[48:51]
	v_exp_f32_e32 v234, v138
	v_exp_f32_e32 v235, v139
	v_mfma_f32_16x16x32_bf16 v[40:43], v[72:75], v[116:119], v[40:43]
	v_exp_f32_e32 v236, v140
	v_exp_f32_e32 v237, v141
	v_mfma_f32_16x16x32_bf16 v[32:35], v[60:63], v[116:119], v[32:35]
	v_exp_f32_e32 v238, v142
	v_exp_f32_e32 v239, v143
	v_mfma_f32_16x16x32_bf16 v[24:27], v[56:59], v[116:119], v[24:27]
	v_exp_f32_e32 v240, v144
	v_exp_f32_e32 v241, v145
	v_mfma_f32_16x16x32_bf16 v[92:95], v[76:79], v[120:123], v[48:51]
	v_exp_f32_e32 v242, v146
	v_exp_f32_e32 v243, v147
	v_mfma_f32_16x16x32_bf16 v[104:107], v[68:71], v[120:123], v[40:43]
	v_exp_f32_e32 v244, v184
	v_exp_f32_e32 v245, v185
	v_mfma_f32_16x16x32_bf16 v[100:103], v[64:67], v[120:123], v[32:35]
	v_exp_f32_e32 v246, v186
	v_exp_f32_e32 v247, v187
	v_mfma_f32_16x16x32_bf16 v[112:115], v[52:55], v[120:123], v[24:27]
	v_pk_add_f32 v[194:195], v[232:233], v[234:235]
	v_pk_add_f32 v[194:195], v[194:195], v[236:237]
	v_pk_add_f32 v[194:195], v[194:195], v[238:239]
	v_pk_add_f32 v[194:195], v[194:195], v[240:241]
	v_pk_add_f32 v[194:195], v[194:195], v[242:243]
	v_pk_add_f32 v[194:195], v[194:195], v[244:245]
	v_pk_add_f32 v[194:195], v[194:195], v[246:247]
	v_add_f32_e32 v194, v194, v195
	v_cmp_lt_f32_e32 vcc, 0x42800000, v194
	s_cbranch_vccnz .Lwin_int_s1
	v_add_f32_e32 v128, v154, v194
	v_cvt_pk_bf16_f32 v136, v232, v233
	v_cvt_pk_bf16_f32 v137, v234, v235
	v_cvt_pk_bf16_f32 v138, v236, v237
	v_cvt_pk_bf16_f32 v139, v238, v239
	v_cvt_pk_bf16_f32 v140, v240, v241
	v_cvt_pk_bf16_f32 v141, v242, v243
	v_cvt_pk_bf16_f32 v142, v244, v245
	v_cvt_pk_bf16_f32 v143, v246, v247
.Lwin_int_p1:
	v_mov_b64_e32 v[158:159], v[156:157]
	v_mfma_f32_16x16x32_bf16 v[44:47], v[80:83], v[136:139], v[44:47]
	v_mfma_f32_16x16x32_bf16 v[36:39], v[72:75], v[136:139], v[36:39]
	v_mfma_f32_16x16x32_bf16 v[28:31], v[60:63], v[136:139], v[28:31]
	v_mfma_f32_16x16x32_bf16 v[20:23], v[56:59], v[136:139], v[20:23]
	v_mfma_f32_16x16x32_bf16 v[84:87], v[76:79], v[140:143], v[44:47]
	v_mfma_f32_16x16x32_bf16 v[96:99], v[68:71], v[140:143], v[36:39]
	v_mfma_f32_16x16x32_bf16 v[88:91], v[64:67], v[140:143], v[28:31]
	v_mfma_f32_16x16x32_bf16 v[108:111], v[52:55], v[140:143], v[20:23]
	s_branch .LBB0_2733
.Lwin_int_e1b:
	v_exp_f32_e32 v232, v136
	v_exp_f32_e32 v233, v137
	v_exp_f32_e32 v234, v138
	v_exp_f32_e32 v235, v139
	v_exp_f32_e32 v236, v140
	v_exp_f32_e32 v237, v141
	v_exp_f32_e32 v238, v142
	v_exp_f32_e32 v239, v143
	v_exp_f32_e32 v240, v144
	v_exp_f32_e32 v241, v145
	v_exp_f32_e32 v242, v146
	v_exp_f32_e32 v243, v147
	v_exp_f32_e32 v244, v184
	v_exp_f32_e32 v245, v185
	v_exp_f32_e32 v246, v186
	v_exp_f32_e32 v247, v187
	v_pk_add_f32 v[194:195], v[232:233], v[234:235]
	v_pk_add_f32 v[194:195], v[194:195], v[236:237]
	v_pk_add_f32 v[194:195], v[194:195], v[238:239]
	v_pk_add_f32 v[194:195], v[194:195], v[240:241]
	v_pk_add_f32 v[194:195], v[194:195], v[242:243]
	v_pk_add_f32 v[194:195], v[194:195], v[244:245]
	v_pk_add_f32 v[194:195], v[194:195], v[246:247]
	v_add_f32_e32 v194, v194, v195
	v_cmp_lt_f32_e32 vcc, 0x42800000, v194
	s_cbranch_vccnz .Lwin_int_s1
	v_add_f32_e32 v128, v154, v194
	v_cvt_pk_bf16_f32 v136, v232, v233
	v_cvt_pk_bf16_f32 v137, v234, v235
	v_cvt_pk_bf16_f32 v138, v236, v237
	v_cvt_pk_bf16_f32 v139, v238, v239
	v_cvt_pk_bf16_f32 v140, v240, v241
	v_cvt_pk_bf16_f32 v141, v242, v243
	v_cvt_pk_bf16_f32 v142, v244, v245
	v_cvt_pk_bf16_f32 v143, v246, v247
	s_branch .Lwin_int_p1
